# P5: RWKV output pass (GroupNorm+bonus+gate) runs on 64 CUs (8 per XCD) concurrently with attention on the other CUs instead of on all CUs before attention
# speedup vs baseline: 1.0761x; 1.0544x over previous
; __device__ __forceinline__ void phase_rwkv_out(const Args& A, int gtid, int NGT) {
;     ...
;     for (int e0 = gtid; e0 < M * (RW / 4); e0 += 4 * NGT) {
;         f32x4 y[4], v0[4], v1[4]; v2u gw[4]; float cf[4]; int mm[4], cc[4]; bool ok[4];
; #pragma unroll
;         for (int q = 0; q < 4; ++q) { const int e = e0 + q * NGT; ok[q] = e < M * (RW / 4); const int ee = ok[q] ? e : e0;
;             const int m = ee / (RW / 4), c4 = (ee % (RW / 4)) * 4, h = c4 >> 6; const int t = m & (T - 1); mm[q] = m; cc[q] = c4;
;             y[q] = __builtin_nontemporal_load((const f32x4*)(Y + (size_t)m * RW + c4));
;             v0[q] = *(const f32x4*)(Vr + (size_t)m * RW + c4); v1[q] = t ? *(const f32x4*)(Vr + (size_t)(m - 1) * RW + c4) : (f32x4){0.f, 0.f, 0.f, 0.f};
;             cf[q] = COEF[(size_t)m * NH + h]; gw[q] = __builtin_nontemporal_load((const v2u*)(G + (size_t)m * 4096 + c4)); }
; __global__ void __launch_bounds__(NWAVES * 64, 2) hybrid_fwd(Args A) {
;     ...
;     if (IN(5)) { PH_IDS
;         phase_rwkv_out(A, gtid, NGT);
.LBB0_636:
	s_mov_b32 s98, s10
	s_mov_b32 s99, s50
	s_cmpk_lg_i32 s50, 0x100
	s_cbranch_scc1 .Lrwk_set
	s_and_b32 s100, s10, 31
	s_cmp_lt_u32 s100, 8
	s_cbranch_scc0 .Lrwk_out
	s_lshr_b32 s101, s10, 5
	s_lshl_b32 s101, s101, 3
	s_or_b32 s10, s101, s100
	s_branch .Lrwk_n
.Lrwk_out:
	s_movk_i32 s10, 0x1800
.Lrwk_n:
	s_movk_i32 s50, 64

; __global__ void __launch_bounds__(NWAVES * 64, 2) hybrid_fwd(Args A) {
;     ...
;         phase_rwkv_out(A, gtid, NGT);
;         __syncthreads();
;         for (int id = vcu; id < 128; id += G) {
;             { pg8::Gemm g{MQh, MKh, 4 * M, 2048, 256}; pg8::ListSched S{id, 1 << 20, 128, 1, 0}; pg8::EpiSoftmax E{Pm, 0.0625f * 1.4426950408889634f};
;               pg8::gemm_phase<pg8::EpiSoftmax, pg8::ListSched, false, PG8_SP2>(lds, g, S, E, TIDNOW); }
.LBB0_653:
	s_or_b64 exec, exec, s[12:13]
	s_mov_b32 s10, s98
	s_mov_b32 s50, s99
	s_mov_b64 s[78:79], s[60:61]
	s_mov_b64 s[76:77], s[56:57]
	s_mov_b64 s[36:37], s[62:63]
	s_cmpk_gt_i32 s10, 0x7f
	s_barrier
	s_cbranch_scc1 .LBB0_700
	s_add_u32 s8, s22, 0x18a00000
	s_addc_u32 s9, s23, 0
	s_add_u32 s39, s22, 0x21200000
	s_addc_u32 s51, s23, 0
	s_add_u32 s52, s22, 0x22200000
	s_addc_u32 s53, s23, 0
	s_add_u32 s54, s22, 0x22300000
	s_addc_u32 s55, s23, 0
	s_add_u32 s56, s22, 0x2ba00000
	s_addc_u32 s57, s23, 0
	s_add_u32 s12, s22, 0x2ca00000
	v_mbcnt_lo_u32_b32 v0, -1, 0
	s_addc_u32 s13, s23, 0
	s_lshl_b32 s58, s10, 3
	s_lshl_b32 s59, s50, 3
	s_lshl_b32 s60, s10, 8
	s_lshl_b32 s61, s50, 8
	s_mov_b32 s11, 0
	v_mov_b32_e32 v129, 0
	s_add_i32 s62, 0, 0x18000
	s_mov_b64 s[14:15], 0x80
	s_add_i32 s63, 0, 0x1c000
	s_mov_b64 s[16:17], 0x100
	s_mov_b64 s[30:31], 0x180
	s_mov_b32 s64, 0xff800000
	s_mov_b32 s38, 0x3db8aa3b
	s_mov_b64 s[40:41], 0x100000
	s_mov_b64 s[42:43], 0x120000
	s_mov_b64 s[44:45], 0x140000
	s_mov_b64 s[46:47], 0x160000
	v_mov_b32_e32 v134, 1
	v_mbcnt_hi_u32_b32 v135, -1, v0
	s_branch .LBB0_657

; __global__ void __launch_bounds__(NWAVES * 64, 2) hybrid_fwd(Args A) {
	.amdhsa_kernel _Z10hybrid_fwd4Args
		.amdhsa_group_segment_fixed_size 0
		.amdhsa_private_segment_fixed_size 0
		.amdhsa_kernarg_size 440
		.amdhsa_user_sgpr_count 2
		.amdhsa_user_sgpr_dispatch_ptr 0
		.amdhsa_user_sgpr_queue_ptr 0
		.amdhsa_user_sgpr_kernarg_segment_ptr 1
		.amdhsa_user_sgpr_dispatch_id 0
		.amdhsa_user_sgpr_kernarg_preload_length 0
		.amdhsa_user_sgpr_kernarg_preload_offset 0
		.amdhsa_user_sgpr_private_segment_size 0
		.amdhsa_uses_dynamic_stack 0
		.amdhsa_enable_private_segment 0
		.amdhsa_system_sgpr_workgroup_id_x 1
		.amdhsa_system_sgpr_workgroup_id_y 0
		.amdhsa_system_sgpr_workgroup_id_z 0
		.amdhsa_system_sgpr_workgroup_info 0
		.amdhsa_system_vgpr_workitem_id 2
		.amdhsa_next_free_vgpr 255
		.amdhsa_next_free_sgpr 102
		.amdhsa_accum_offset 256
		.amdhsa_reserve_vcc 1
		.amdhsa_float_round_mode_32 0
		.amdhsa_float_round_mode_16_64 0
		.amdhsa_float_denorm_mode_32 3
		.amdhsa_float_denorm_mode_16_64 3
		.amdhsa_dx10_clamp 1
		.amdhsa_ieee_mode 1
		.amdhsa_fp16_overflow 0
		.amdhsa_tg_split 0
		.amdhsa_exception_fp_ieee_invalid_op 0
		.amdhsa_exception_fp_denorm_src 0
		.amdhsa_exception_fp_ieee_div_zero 0
		.amdhsa_exception_fp_ieee_overflow 0
		.amdhsa_exception_fp_ieee_underflow 0
		.amdhsa_exception_fp_ieee_inexact 0
		.amdhsa_exception_int_div_zero 0
	.end_amdhsa_kernel

; __global__ void __launch_bounds__(NWAVES * 64, 2) hybrid_fwd(Args A) {
amdhsa.kernels:
  - .agpr_count:     0
    .args:
      - .offset:         0
        .size:           184
        .value_kind:     by_value
      - .offset:         184
        .size:           4
        .value_kind:     hidden_block_count_x
      - .offset:         188
        .size:           4
        .value_kind:     hidden_block_count_y
      - .offset:         192
        .size:           4
        .value_kind:     hidden_block_count_z
      - .offset:         196
        .size:           2
        .value_kind:     hidden_group_size_x
      - .offset:         198
        .size:           2
        .value_kind:     hidden_group_size_y
      - .offset:         200
        .size:           2
        .value_kind:     hidden_group_size_z
      - .offset:         202
        .size:           2
        .value_kind:     hidden_remainder_x
      - .offset:         204
        .size:           2
        .value_kind:     hidden_remainder_y
      - .offset:         206
        .size:           2
        .value_kind:     hidden_remainder_z
      - .offset:         224
        .size:           8
        .value_kind:     hidden_global_offset_x
      - .offset:         232
        .size:           8
        .value_kind:     hidden_global_offset_y
      - .offset:         240
        .size:           8
        .value_kind:     hidden_global_offset_z
      - .offset:         248
        .size:           2
        .value_kind:     hidden_grid_dims
      - .offset:         272
        .size:           8
        .value_kind:     hidden_multigrid_sync_arg
      - .offset:         304
        .size:           4
        .value_kind:     hidden_dynamic_lds_size
    .group_segment_fixed_size: 0
    .kernarg_segment_align: 8
    .kernarg_segment_size: 440
    .language:       OpenCL C
    .language_version:
      - 2
      - 0
    .max_flat_workgroup_size: 512
    .name:           _Z10hybrid_fwd4Args
    .private_segment_fixed_size: 0
    .sgpr_count:     108
    .sgpr_spill_count: 34
    .symbol:         _Z10hybrid_fwd4Args.kd
    .uniform_work_group_size: 1
    .uses_dynamic_stack: false
    .vgpr_count:     255
    .vgpr_spill_count: 0
    .wavefront_size: 64
